# v-side: per-token sort of the 128 experts by v-table slice (alternating direction) for L2 locality
# speedup vs baseline: 1.1606x; 1.0091x over previous
; __device__ void phase_gather(const Params& p) {
;     ...
;   for (int t = blockIdx.x * 8 + wid; t < T_TOK; t += gridDim.x * 8) {
;     const int id0 = idxg[(size_t)t * 128 + lane], id1 = idxg[(size_t)t * 128 + 64 + lane];
;     const float g0 = gg[(size_t)t * 128 + lane], g1 = gg[(size_t)t * 128 + 64 + lane];
;     const float su0 = scales[id0], su1 = scales[id1], sv0 = scales[16384 + id0], sv1 = scales[16384 + id1];
;     float* orow = p.out + (size_t)t * DM + lane * 32;
;     const float sx = ((const float*)(ws + OFF_WBUF + 8 * MIB))[t];
;     float sq = (lane < 32) ? ssq2[(size_t)t * 32 + lane] : 0.f;
;     sq = wave_sum(sq);
;     const float rs2 = rsqrtf(sq * (1.f / 2048.f) + EPSV);
;     const int* wbuf = (const int*)(ws + OFF_WBUF);
;     const int d0 = wbuf[(size_t)t * 128 + lane], d1 = wbuf[(size_t)t * 128 + 64 + lane];
;     const float w0 = gelu_((float)d0 * (su0 * sx * rs2)) * g0 * sv0;
;     const float w1 = gelu_((float)d1 * (su1 * sx * rs2)) * g1 * sv1;
;     float wmax = fmaxf(fabsf(w0), fabsf(w1));
; #pragma unroll
;     for (int o = 32; o > 0; o >>= 1) wmax = fmaxf(wmax, __shfl_xor(wmax, o));
;     const float sw = wmax * (1.f / 127.f);
;     const float winv = wmax > 0.f ? 127.f / wmax : 0.f;
.LBB0_1320:
	s_or_b64 exec, exec, s[0:1]
	v_lshl_add_u64 v[0:1], v[0:1], 2, s[70:71]
	v_lshl_add_u64 v[2:3], v[2:3], 2, s[70:71]
	global_load_dword v4, v[0:1], off
	global_load_dword v5, v[2:3], off
	s_waitcnt vmcnt(2)
	ds_bpermute_b32 v0, v126, v13
	v_mul_f32_e32 v2, v11, v10
	s_mov_b32 s4, 0x42fe0000
	s_mov_b64 s[0:1], -1
	v_mov_b32_e32 v163, 0
	s_waitcnt lgkmcnt(0)
	v_add_f32_e32 v0, v13, v0
	ds_bpermute_b32 v1, v127, v0
	v_mov_b32_e32 v164, 0
	v_mov_b32_e32 v161, 0
	v_mov_b32_e32 v162, 0
	v_mov_b32_e32 v159, 0
	s_waitcnt lgkmcnt(0)
	v_add_f32_e32 v0, v0, v1
	ds_bpermute_b32 v1, v128, v0
	v_mov_b32_e32 v160, 0
	v_mov_b32_e32 v157, 0
	v_mov_b32_e32 v158, 0
	v_mov_b32_e32 v152, 0
	s_waitcnt lgkmcnt(0)
	v_add_f32_e32 v0, v0, v1
	ds_bpermute_b32 v1, v129, v0
	v_mov_b32_e32 v154, 0
	v_mov_b32_e32 v149, 0
	v_mov_b32_e32 v150, 0
	v_mov_b32_e32 v144, 0
	s_waitcnt lgkmcnt(0)
	v_add_f32_e32 v0, v0, v1
	ds_bpermute_b32 v1, v130, v0
	v_mov_b32_e32 v146, 0
	v_mov_b32_e32 v155, 0
	v_mov_b32_e32 v156, 0
	v_mov_b32_e32 v151, 0
	s_waitcnt lgkmcnt(0)
	v_add_f32_e32 v0, v0, v1
	ds_bpermute_b32 v1, v131, v0
	v_mov_b32_e32 v153, 0
	v_mov_b32_e32 v147, 0
	v_mov_b32_e32 v148, 0
	v_mov_b32_e32 v143, 0
	s_waitcnt lgkmcnt(0)
	v_add_f32_e32 v0, v0, v1
	v_fmamk_f32 v0, v0, 0x3a000000, v133
	v_mul_f32_e32 v1, 0x4b800000, v0
	v_cmp_gt_f32_e32 vcc, s55, v0
	v_mov_b32_e32 v145, 0
	v_mov_b32_e32 v141, 0
	v_cndmask_b32_e32 v0, v0, v1, vcc
	v_rsq_f32_e32 v0, v0
	v_mul_f32_e32 v1, v12, v10
	v_mov_b32_e32 v142, 0
	v_mov_b32_e32 v136, 0
	v_mul_f32_e32 v3, 0x45800000, v0
	v_cndmask_b32_e32 v0, v0, v3, vcc
	v_mul_f32_e32 v1, v1, v0
	v_mul_f32_e32 v0, v2, v0
	v_mov_b32_e32 v140, 0
	v_mov_b32_e32 v137, 0
	v_mov_b32_e32 v139, 0
	v_mov_b32_e32 v134, 0
	v_mov_b32_e32 v135, 0
	v_mov_b32_e32 v123, 0
	v_mov_b32_e32 v125, 0
	s_waitcnt vmcnt(1)
	v_cvt_f32_i32_e32 v3, v4
	s_waitcnt vmcnt(0)
	v_cvt_f32_i32_e32 v4, v5
	v_mul_f32_e32 v1, v1, v3
	v_mul_f32_e32 v0, v0, v4
	v_mul_f32_e32 v2, 0x3d372713, v1
	v_mul_f32_e32 v3, 0x3d372713, v0
	v_mul_f32_e32 v2, v1, v2
	v_mul_f32_e32 v3, v0, v3
	v_fma_f32 v2, v1, v2, v1
	v_fma_f32 v3, v0, v3, v0
	v_mul_f32_e32 v2, 0x3f4c422a, v2
	v_mul_f32_e32 v3, 0x3f4c422a, v3
	v_add_f32_e32 v2, v2, v2
	v_add_f32_e32 v3, v3, v3
	v_mul_f32_e32 v2, 0xbfb8aa3b, v2
	v_mul_f32_e32 v3, 0xbfb8aa3b, v3
	v_exp_f32_e32 v2, v2
	v_exp_f32_e32 v3, v3
	v_add_f32_e32 v2, 1.0, v2
	v_add_f32_e32 v3, 1.0, v3
	v_rcp_f32_e32 v2, v2
	v_rcp_f32_e32 v3, v3
	v_mul_f32_e32 v1, v1, v2
	v_mul_f32_e32 v0, v0, v3
	v_mul_f32_e32 v1, v6, v1
	v_mul_f32_e32 v0, v7, v0
	v_mul_f32_e32 v1, v8, v1
	v_mul_f32_e32 v0, v9, v0
	v_max_f32_e64 v2, |v1|, |v0|
	ds_bpermute_b32 v3, v126, v2
	s_waitcnt lgkmcnt(0)
	v_max_f32_e32 v3, v3, v3
	v_max_f32_e32 v2, v2, v3
	ds_bpermute_b32 v3, v127, v2
	s_waitcnt lgkmcnt(0)
	v_max_f32_e32 v3, v3, v3
	v_max_f32_e32 v2, v2, v3
	ds_bpermute_b32 v3, v128, v2
	s_waitcnt lgkmcnt(0)
	v_max_f32_e32 v3, v3, v3
	v_max_f32_e32 v2, v2, v3
	ds_bpermute_b32 v3, v129, v2
	s_waitcnt lgkmcnt(0)
	v_max_f32_e32 v3, v3, v3
	v_max_f32_e32 v2, v2, v3
	ds_bpermute_b32 v3, v130, v2
	s_waitcnt lgkmcnt(0)
	v_max_f32_e32 v3, v3, v3
	v_max_f32_e32 v2, v2, v3
	ds_bpermute_b32 v3, v131, v2
	s_waitcnt lgkmcnt(0)
; __device__ void phase_gather(const Params& p) {
;     ...
;     float wmax = fmaxf(fabsf(w0), fabsf(w1));
; #pragma unroll
;     for (int o = 32; o > 0; o >>= 1) wmax = fmaxf(wmax, __shfl_xor(wmax, o));
;     const float sw = wmax * (1.f / 127.f);
;     const float winv = wmax > 0.f ? 127.f / wmax : 0.f;
;     const int q0 = __float2int_rn(w0 * winv), q1 = __float2int_rn(w1 * winv);
;     int wsumq = q0 + q1;
; #pragma unroll
;     for (int o = 32; o > 0; o >>= 1) wsumq += __shfl_xor(wsumq, o);
;     int pk0 = (int)(((unsigned)q0 & 0xffu) << (8 * (lane & 3))), pk1 = (int)(((unsigned)q1 & 0xffu) << (8 * (lane & 3)));
;     pk0 |= __shfl_xor(pk0, 1); pk0 |= __shfl_xor(pk0, 2);
;     pk1 |= __shfl_xor(pk1, 1); pk1 |= __shfl_xor(pk1, 2);
	v_max_f32_e32 v3, v3, v3
	v_max_f32_e32 v165, v2, v3
	v_div_scale_f32 v2, s[2:3], v165, v165, s4
	v_rcp_f32_e32 v3, v2
	v_div_scale_f32 v4, vcc, s4, v165, s4
	v_fma_f32 v5, -v2, v3, 1.0
	v_fmac_f32_e32 v3, v5, v3
	v_mul_f32_e32 v5, v4, v3
	v_fma_f32 v6, -v2, v5, v4
	v_fmac_f32_e32 v5, v6, v3
	v_fma_f32 v2, -v2, v5, v4
	v_div_fmas_f32 v2, v2, v3, v5
	v_div_fixup_f32 v2, v2, v165, s4
	v_cmp_lt_f32_e32 vcc, 0, v165
	s_nop 1
	v_cndmask_b32_e32 v2, 0, v2, vcc
	v_mul_f32_e32 v1, v1, v2
	v_mul_f32_e32 v0, v0, v2
	v_rndne_f32_e32 v1, v1
	v_rndne_f32_e32 v0, v0
	v_cvt_i32_f32_e32 v1, v1
	v_cvt_i32_f32_e32 v0, v0
	v_bfe_i32 v222, v112, 11, 1
	v_and_b32_e32 v222, 3, v222
	v_lshrrev_b32_e32 v216, 12, v122
	v_lshrrev_b32_e32 v217, 12, v124
	v_xor_b32_e32 v216, v216, v222
	v_xor_b32_e32 v217, v217, v222
	v_and_b32_e32 v225, 7, v112
	v_lshlrev_b32_e32 v225, 10, v225
	v_lshl_add_u32 v226, v138, 2, v225
	s_mov_b32 s86, 0
	v_mov_b32_e32 v218, 0
	v_mov_b32_e32 v219, 0
	v_cmp_eq_u32_e64 s[82:83], 0, v216
	v_cmp_eq_u32_e64 s[84:85], 0, v217
	s_nop 3
	v_mbcnt_lo_u32_b32 v220, s82, 0
	v_mbcnt_hi_u32_b32 v220, s83, v220
	v_mbcnt_lo_u32_b32 v221, s84, 0
	v_mbcnt_hi_u32_b32 v221, s85, v221
	s_bcnt1_i32_b64 s87, s[82:83]
	s_bcnt1_i32_b64 s56, s[84:85]
	v_add_u32_e32 v220, s86, v220
	s_add_i32 s86, s86, s87
	v_add_u32_e32 v221, s86, v221
	s_add_i32 s86, s86, s56
	v_cndmask_b32_e64 v218, v218, v220, s[82:83]
	v_cndmask_b32_e64 v219, v219, v221, s[84:85]
	v_cmp_eq_u32_e64 s[82:83], 1, v216
	v_cmp_eq_u32_e64 s[84:85], 1, v217
	s_nop 3
	v_mbcnt_lo_u32_b32 v220, s82, 0
	v_mbcnt_hi_u32_b32 v220, s83, v220
	v_mbcnt_lo_u32_b32 v221, s84, 0
	v_mbcnt_hi_u32_b32 v221, s85, v221
	s_bcnt1_i32_b64 s87, s[82:83]
	s_bcnt1_i32_b64 s56, s[84:85]
	v_add_u32_e32 v220, s86, v220
	s_add_i32 s86, s86, s87
	v_add_u32_e32 v221, s86, v221
	s_add_i32 s86, s86, s56
	v_cndmask_b32_e64 v218, v218, v220, s[82:83]
	v_cndmask_b32_e64 v219, v219, v221, s[84:85]
	v_cmp_eq_u32_e64 s[82:83], 2, v216
	v_cmp_eq_u32_e64 s[84:85], 2, v217
	s_nop 3
	v_mbcnt_lo_u32_b32 v220, s82, 0
	v_mbcnt_hi_u32_b32 v220, s83, v220
	v_mbcnt_lo_u32_b32 v221, s84, 0
	v_mbcnt_hi_u32_b32 v221, s85, v221
	s_bcnt1_i32_b64 s87, s[82:83]
	s_bcnt1_i32_b64 s56, s[84:85]
	v_add_u32_e32 v220, s86, v220
	s_add_i32 s86, s86, s87
	v_add_u32_e32 v221, s86, v221
	s_add_i32 s86, s86, s56
	v_cndmask_b32_e64 v218, v218, v220, s[82:83]
	v_cndmask_b32_e64 v219, v219, v221, s[84:85]
	v_cmp_eq_u32_e64 s[82:83], 3, v216
	v_cmp_eq_u32_e64 s[84:85], 3, v217
	s_nop 3
	v_mbcnt_lo_u32_b32 v220, s82, 0
	v_mbcnt_hi_u32_b32 v220, s83, v220
	v_mbcnt_lo_u32_b32 v221, s84, 0
	v_mbcnt_hi_u32_b32 v221, s85, v221
	s_bcnt1_i32_b64 s87, s[82:83]
	s_bcnt1_i32_b64 s56, s[84:85]
	v_add_u32_e32 v220, s86, v220
	s_add_i32 s86, s86, s87
	v_add_u32_e32 v221, s86, v221
	s_add_i32 s86, s86, s56
	v_cndmask_b32_e64 v218, v218, v220, s[82:83]
	v_cndmask_b32_e64 v219, v219, v221, s[84:85]
	v_and_b32_e32 v220, 0xff, v1
	v_and_b32_e32 v221, 0xff, v0
	v_lshl_or_b32 v223, v122, 8, v220
	v_lshl_or_b32 v224, v124, 8, v221
	v_lshl_add_u32 v218, v218, 2, v225
	v_lshl_add_u32 v219, v219, 2, v225
	ds_write_b32 v218, v223
	ds_write_b32 v219, v224
	s_waitcnt lgkmcnt(0)
	ds_read_b32 v223, v226
	ds_read_b32 v224, v226 offset:256
	s_waitcnt lgkmcnt(0)
	v_lshrrev_b32_e32 v122, 8, v223
	v_lshrrev_b32_e32 v124, 8, v224
	v_bfe_i32 v1, v223, 0, 8
	v_bfe_i32 v0, v224, 0, 8
	v_add_u32_e32 v2, v1, v0
	ds_bpermute_b32 v3, v126, v2
	v_lshlrev_b32_sdwa v1, v132, v1 dst_sel:DWORD dst_unused:UNUSED_PAD src0_sel:DWORD src1_sel:BYTE_0
	v_lshlrev_b32_sdwa v0, v132, v0 dst_sel:DWORD dst_unused:UNUSED_PAD src0_sel:DWORD src1_sel:BYTE_0
	ds_bpermute_b32 v4, v131, v1
	ds_bpermute_b32 v5, v131, v0
	s_waitcnt lgkmcnt(2)
	v_add_u32_e32 v2, v2, v3
	ds_bpermute_b32 v3, v127, v2
	s_waitcnt lgkmcnt(2)
	v_or_b32_e32 v1, v1, v4
	s_waitcnt lgkmcnt(1)
	v_or_b32_e32 v0, v0, v5
	ds_bpermute_b32 v4, v130, v1
	s_waitcnt lgkmcnt(1)
	v_add_u32_e32 v2, v2, v3
	ds_bpermute_b32 v3, v128, v2
	ds_bpermute_b32 v5, v130, v0
	s_waitcnt lgkmcnt(2)
	v_or_b32_e32 v168, v1, v4
	s_waitcnt lgkmcnt(1)
	v_add_u32_e32 v2, v2, v3
	ds_bpermute_b32 v3, v129, v2
	s_waitcnt lgkmcnt(1)
	v_or_b32_e32 v169, v0, v5
	s_waitcnt lgkmcnt(0)
	v_add_u32_e32 v2, v2, v3
	ds_bpermute_b32 v3, v130, v2
	s_waitcnt lgkmcnt(0)
	v_add_u32_e32 v166, v2, v3
	ds_bpermute_b32 v167, v131, v166
